# RESID/PLE epilogue: nontemporal stores for the f32 residual stream (not re-read until several phases later)
# baseline (speedup 1.0000x reference)
; DI unsigned pk2(float lo, float hi) { const f32x2v v = {lo, hi}; const bf16x2v b = __builtin_convertvector(v, bf16x2v); return __builtin_bit_cast(unsigned, b); }
; DI float sigmoidf_(float x) { return __builtin_amdgcn_rcpf(1.0f + __expf(-x)); }
; DI void unpack8(const u32x4& w, float* f) { f[0] = bflo(w.x); f[1] = bfhi(w.x); f[2] = bflo(w.y); f[3] = bfhi(w.y); f[4] = bflo(w.z); f[5] = bfhi(w.z); f[6] = bflo(w.w); f[7] = bfhi(w.w); }
; DI float rs_of(float ss, float inv_n) { return __builtin_amdgcn_rsqf(ss * inv_n + EPS); }
; DI float sum16_fq(const float* p, int fq) { const f32x4 a = *(const f32x4*)(p + 4 * fq); float s = (a[0] + a[1]) + (a[2] + a[3]); s += __shfl_xor(s, 16); s += __shfl_xor(s, 32); return s; }
; DI void epilogue(int kind, int l, const f32x4 (&acc)[2][2][4][2], const Unit& u, int wr, int wc, int fr, int fq) {
;     ...
;             for (int m = 0; m < 4; ++m) { const int row = row0 + ai * HALF + m * 16; float sq = 0.f;
;                 const float rs = ple ? rs_of(sum16_fq(E.ss_in + (size_t)row * 16, fq), 1.f / 1024.f) : 0.f;
; #pragma unroll
;                 for (int bj = 0; bj < 2; ++bj) { const int col = col0 + bj * HALF; float* xp = E.x + (size_t)row * DM + col; const float* xi = E.xin + (size_t)row * DM + col;
;                     f32x4 x0 = *(const f32x4*)xi, x1 = *(const f32x4*)(xi + 4); f32x4 v0 = acc[ai][bj][m][0], v1 = acc[ai][bj][m][1];
;                     if (ple) { const u32x4 pw = *(const u32x4*)(E.ppb + (size_t)row * DM + col); float pf[8]; unpack8(pw, pf);
; #pragma unroll
;                         for (int j = 0; j < 4; ++j) { x0[j] += sigmoidf_(v0[j] * rs) * pf[j] * E.alpha; x1[j] += sigmoidf_(v1[j] * rs) * pf[4 + j] * E.alpha; }
;                     } else if (E.cs) { const f32x4 c0 = *(const f32x4*)(E.cs + col), c1 = *(const f32x4*)(E.cs + col + 4); x0 += v0 * c0 * E.alpha; x1 += v1 * c1 * E.alpha; }
;                     else { x0 += v0 * E.alpha; x1 += v1 * E.alpha; }
;                     *(f32x4*)xp = x0; *(f32x4*)(xp + 4) = x1;
;                     u32x4 w; w.x = pk2(x0[0], x0[1]); w.y = pk2(x0[2], x0[3]); w.z = pk2(x1[0], x1[1]); w.w = pk2(x1[2], x1[3]);
;                     *(u32x4*)(E.xb + (size_t)row * DM + col) = w;
;                     sq += (x0[0] * x0[0] + x0[1] * x0[1]) + (x0[2] * x0[2] + x0[3] * x0[3]) + (x1[0] * x1[0] + x1[1] * x1[1]) + (x1[2] * x1[2] + x1[3] * x1[3]); }
.LBB0_675:
	s_add_u32 s8, s8, s10
	s_waitcnt vmcnt(0)
	v_lshlrev_b64 v[138:139], 10, v[172:173]
	s_addc_u32 s9, s9, s11
	v_lshl_add_u64 v[140:141], v[138:139], 2, s[90:91]
	v_lshl_add_u64 v[142:143], v[138:139], 1, s[8:9]
	v_lshl_add_u64 v[180:181], v[174:175], 2, v[140:141]
	v_cvt_pk_bf16_f32 v138, v130, v131
	v_cvt_pk_bf16_f32 v139, v132, v133
	v_cvt_pk_bf16_f32 v140, v134, v135
	v_cvt_pk_bf16_f32 v141, v136, v137
	v_lshl_add_u64 v[182:183], v[174:175], 1, v[142:143]
	global_store_dwordx4 v[180:181], v[130:133], off nt
	global_store_dwordx4 v[180:181], v[134:137], off offset:16 nt
	global_store_dwordx4 v[182:183], v[138:141], off
	global_load_dwordx4 v[138:141], v[150:151], off offset:528
	s_nop 0
	global_load_dwordx4 v[150:153], v[150:151], off offset:512
	v_cndmask_b32_e64 v142, 0, 1, s[12:13]
	v_cmp_ne_u32_e64 s[46:47], 1, v142
	s_andn2_b64 vcc, exec, s[12:13]
	s_mov_b64 s[10:11], -1
	s_cbranch_vccnz .LBB0_680
	s_and_b64 vcc, exec, s[42:43]
	s_cbranch_vccnz .LBB0_818
	v_lshl_add_u64 v[146:147], v[174:175], 2, s[94:95]
	global_load_dwordx4 v[142:145], v[146:147], off offset:512
	s_nop 0
	global_load_dwordx4 v[146:149], v[146:147], off offset:528
	s_mov_b32 s10, s92
	s_mov_b32 s11, s92
	s_waitcnt vmcnt(1)
	v_pk_mul_f32 v[144:145], v[120:121], v[144:145]
	v_pk_mul_f32 v[142:143], v[118:119], v[142:143]
	s_waitcnt vmcnt(0)
	v_pk_mul_f32 v[148:149], v[116:117], v[148:149]
	v_pk_mul_f32 v[146:147], v[114:115], v[146:147]
	v_pk_fma_f32 v[144:145], s[10:11], v[144:145], v[152:153]
	v_pk_fma_f32 v[142:143], s[92:93], v[142:143], v[150:151]
	v_pk_fma_f32 v[148:149], s[10:11], v[148:149], v[140:141]
	v_pk_fma_f32 v[146:147], s[92:93], v[146:147], v[138:139]
	s_cbranch_execnz .LBB0_679

; DI unsigned pk2(float lo, float hi) { const f32x2v v = {lo, hi}; const bf16x2v b = __builtin_convertvector(v, bf16x2v); return __builtin_bit_cast(unsigned, b); }
; DI float sigmoidf_(float x) { return __builtin_amdgcn_rcpf(1.0f + __expf(-x)); }
; DI void unpack8(const u32x4& w, float* f) { f[0] = bflo(w.x); f[1] = bfhi(w.x); f[2] = bflo(w.y); f[3] = bfhi(w.y); f[4] = bflo(w.z); f[5] = bfhi(w.z); f[6] = bflo(w.w); f[7] = bfhi(w.w); }
; DI void epilogue(int kind, int l, const f32x4 (&acc)[2][2][4][2], const Unit& u, int wr, int wc, int fr, int fq) {
;     ...
;                 for (int bj = 0; bj < 2; ++bj) { const int col = col0 + bj * HALF; float* xp = E.x + (size_t)row * DM + col; const float* xi = E.xin + (size_t)row * DM + col;
;                     f32x4 x0 = *(const f32x4*)xi, x1 = *(const f32x4*)(xi + 4); f32x4 v0 = acc[ai][bj][m][0], v1 = acc[ai][bj][m][1];
;                     if (ple) { const u32x4 pw = *(const u32x4*)(E.ppb + (size_t)row * DM + col); float pf[8]; unpack8(pw, pf);
; #pragma unroll
;                         for (int j = 0; j < 4; ++j) { x0[j] += sigmoidf_(v0[j] * rs) * pf[j] * E.alpha; x1[j] += sigmoidf_(v1[j] * rs) * pf[4 + j] * E.alpha; }
;                     } else if (E.cs) { const f32x4 c0 = *(const f32x4*)(E.cs + col), c1 = *(const f32x4*)(E.cs + col + 4); x0 += v0 * c0 * E.alpha; x1 += v1 * c1 * E.alpha; }
;                     else { x0 += v0 * E.alpha; x1 += v1 * E.alpha; }
;                     *(f32x4*)xp = x0; *(f32x4*)(xp + 4) = x1;
;                     u32x4 w; w.x = pk2(x0[0], x0[1]); w.y = pk2(x0[2], x0[3]); w.z = pk2(x1[0], x1[1]); w.w = pk2(x1[2], x1[3]);
;                     *(u32x4*)(E.xb + (size_t)row * DM + col) = w;
;                     sq += (x0[0] * x0[0] + x0[1] * x0[1]) + (x0[2] * x0[2] + x0[3] * x0[3]) + (x1[0] * x1[0] + x1[1] * x1[1]) + (x1[2] * x1[2] + x1[3] * x1[3]); }
;                 sq += __shfl_xor(sq, 16); sq += __shfl_xor(sq, 32);
;                 if (fq == 0) E.ss_out[(size_t)row * 16 + u.pn * 4 + wc] = sq; }
.LBB0_682:
	v_mul_f32_e32 v24, v131, v131
	v_fmac_f32_e32 v24, v130, v130
	v_mul_f32_e32 v130, v133, v133
	v_fmac_f32_e32 v130, v132, v132
	v_add_f32_e32 v24, v24, v130
	v_mul_f32_e32 v130, v135, v135
	v_fmac_f32_e32 v130, v134, v134
	v_add_f32_e32 v24, v130, v24
	v_mul_f32_e32 v130, v137, v137
	v_fmac_f32_e32 v130, v136, v136
	v_add_f32_e32 v24, v130, v24
	v_mul_f32_e32 v130, v143, v143
	v_mul_f32_e32 v131, v145, v145
	v_fmac_f32_e32 v130, v142, v142
	v_fmac_f32_e32 v131, v144, v144
	v_add_f32_e32 v130, v130, v131
	v_mul_f32_e32 v131, v147, v147
	v_fmac_f32_e32 v131, v146, v146
	v_add_f32_e32 v130, v131, v130
	v_mul_f32_e32 v131, v149, v149
	v_fmac_f32_e32 v131, v148, v148
	v_add_f32_e32 v130, v131, v130
	v_add_f32_e32 v24, v24, v130
	ds_bpermute_b32 v130, v217, v24
	s_lshl_b32 s10, s64, 2
	s_ashr_i32 s11, s10, 31
	s_lshl_b64 s[10:11], s[10:11], 2
	s_add_u32 s6, s6, s10
	s_waitcnt lgkmcnt(0)
	v_add_f32_e32 v24, v24, v130
	ds_bpermute_b32 v130, v216, v24
	s_addc_u32 s7, s7, s11
	v_readlane_b32 s10, v255, 53
	s_add_u32 s6, s6, s10
	s_addc_u32 s7, s7, 0
	v_cvt_pk_bf16_f32 v132, v142, v143
	v_cvt_pk_bf16_f32 v133, v144, v145
	v_cvt_pk_bf16_f32 v134, v146, v147
	v_cvt_pk_bf16_f32 v135, v148, v149
	global_store_dwordx4 v[180:181], v[142:145], off offset:512 nt
	global_store_dwordx4 v[180:181], v[146:149], off offset:528 nt
	global_store_dwordx4 v[182:183], v[132:135], off offset:256
	s_and_saveexec_b64 s[10:11], s[38:39]
	s_cbranch_execz .LBB0_684
	v_lshl_add_u64 v[132:133], s[6:7], 0, v[178:179]
	s_waitcnt lgkmcnt(0)
	v_add_f32_e32 v24, v24, v130
	global_store_dword v[132:133], v24, off

; DI unsigned pk2(float lo, float hi) { const f32x2v v = {lo, hi}; const bf16x2v b = __builtin_convertvector(v, bf16x2v); return __builtin_bit_cast(unsigned, b); }
; DI float sigmoidf_(float x) { return __builtin_amdgcn_rcpf(1.0f + __expf(-x)); }
; DI void unpack8(const u32x4& w, float* f) { f[0] = bflo(w.x); f[1] = bfhi(w.x); f[2] = bflo(w.y); f[3] = bfhi(w.y); f[4] = bflo(w.z); f[5] = bfhi(w.z); f[6] = bflo(w.w); f[7] = bfhi(w.w); }
; DI float rs_of(float ss, float inv_n) { return __builtin_amdgcn_rsqf(ss * inv_n + EPS); }
; DI float sum16_fq(const float* p, int fq) { const f32x4 a = *(const f32x4*)(p + 4 * fq); float s = (a[0] + a[1]) + (a[2] + a[3]); s += __shfl_xor(s, 16); s += __shfl_xor(s, 32); return s; }
; DI void epilogue(int kind, int l, const f32x4 (&acc)[2][2][4][2], const Unit& u, int wr, int wc, int fr, int fq) {
;     ...
;             for (int m = 0; m < 4; ++m) { const int row = row0 + ai * HALF + m * 16; float sq = 0.f;
;                 const float rs = ple ? rs_of(sum16_fq(E.ss_in + (size_t)row * 16, fq), 1.f / 1024.f) : 0.f;
; #pragma unroll
;                 for (int bj = 0; bj < 2; ++bj) { const int col = col0 + bj * HALF; float* xp = E.x + (size_t)row * DM + col; const float* xi = E.xin + (size_t)row * DM + col;
;                     f32x4 x0 = *(const f32x4*)xi, x1 = *(const f32x4*)(xi + 4); f32x4 v0 = acc[ai][bj][m][0], v1 = acc[ai][bj][m][1];
;                     if (ple) { const u32x4 pw = *(const u32x4*)(E.ppb + (size_t)row * DM + col); float pf[8]; unpack8(pw, pf);
; #pragma unroll
;                         for (int j = 0; j < 4; ++j) { x0[j] += sigmoidf_(v0[j] * rs) * pf[j] * E.alpha; x1[j] += sigmoidf_(v1[j] * rs) * pf[4 + j] * E.alpha; }
;                     } else if (E.cs) { const f32x4 c0 = *(const f32x4*)(E.cs + col), c1 = *(const f32x4*)(E.cs + col + 4); x0 += v0 * c0 * E.alpha; x1 += v1 * c1 * E.alpha; }
;                     else { x0 += v0 * E.alpha; x1 += v1 * E.alpha; }
;                     *(f32x4*)xp = x0; *(f32x4*)(xp + 4) = x1;
;                     u32x4 w; w.x = pk2(x0[0], x0[1]); w.y = pk2(x0[2], x0[3]); w.z = pk2(x1[0], x1[1]); w.w = pk2(x1[2], x1[3]);
;                     *(u32x4*)(E.xb + (size_t)row * DM + col) = w;
;                     sq += (x0[0] * x0[0] + x0[1] * x0[1]) + (x0[2] * x0[2] + x0[3] * x0[3]) + (x1[0] * x1[0] + x1[1] * x1[1]) + (x1[2] * x1[2] + x1[3] * x1[3]); }
.LBB0_693:
	s_waitcnt vmcnt(1)
	v_lshlrev_b64 v[138:139], 10, v[150:151]
	v_lshl_add_u64 v[140:141], v[138:139], 2, s[90:91]
	s_waitcnt vmcnt(0)
	v_lshl_add_u64 v[142:143], v[138:139], 1, s[8:9]
	v_lshl_add_u64 v[180:181], v[174:175], 2, v[140:141]
	v_cvt_pk_bf16_f32 v138, v130, v131
	v_cvt_pk_bf16_f32 v139, v132, v133
	v_cvt_pk_bf16_f32 v140, v134, v135
	v_cvt_pk_bf16_f32 v141, v136, v137
	v_lshl_add_u64 v[182:183], v[174:175], 1, v[142:143]
	global_store_dwordx4 v[180:181], v[130:133], off nt
	global_store_dwordx4 v[180:181], v[134:137], off offset:16 nt
	global_store_dwordx4 v[182:183], v[138:141], off
	global_load_dwordx4 v[138:141], v[152:153], off offset:528
	s_nop 0
	global_load_dwordx4 v[150:153], v[152:153], off offset:512
	s_and_b64 vcc, exec, s[46:47]
	s_mov_b64 s[10:11], -1
	s_cbranch_vccnz .LBB0_698
	s_and_b64 vcc, exec, s[42:43]
	s_cbranch_vccnz .LBB0_820
	v_lshl_add_u64 v[146:147], v[174:175], 2, s[94:95]
	global_load_dwordx4 v[142:145], v[146:147], off offset:512
	s_nop 0
	global_load_dwordx4 v[146:149], v[146:147], off offset:528
	s_mov_b32 s10, s92
	s_mov_b32 s11, s92
	s_waitcnt vmcnt(1)
	v_pk_mul_f32 v[144:145], v[104:105], v[144:145]
	v_pk_mul_f32 v[142:143], v[102:103], v[142:143]
	s_waitcnt vmcnt(0)
	v_pk_mul_f32 v[148:149], v[100:101], v[148:149]
	v_pk_mul_f32 v[146:147], v[98:99], v[146:147]
	v_pk_fma_f32 v[144:145], s[10:11], v[144:145], v[152:153]
	v_pk_fma_f32 v[142:143], s[92:93], v[142:143], v[150:151]
	v_pk_fma_f32 v[148:149], s[10:11], v[148:149], v[140:141]
	v_pk_fma_f32 v[146:147], s[92:93], v[146:147], v[138:139]
	s_cbranch_execnz .LBB0_697

; DI unsigned pk2(float lo, float hi) { const f32x2v v = {lo, hi}; const bf16x2v b = __builtin_convertvector(v, bf16x2v); return __builtin_bit_cast(unsigned, b); }
; DI float sigmoidf_(float x) { return __builtin_amdgcn_rcpf(1.0f + __expf(-x)); }
; DI void unpack8(const u32x4& w, float* f) { f[0] = bflo(w.x); f[1] = bfhi(w.x); f[2] = bflo(w.y); f[3] = bfhi(w.y); f[4] = bflo(w.z); f[5] = bfhi(w.z); f[6] = bflo(w.w); f[7] = bfhi(w.w); }
; DI void epilogue(int kind, int l, const f32x4 (&acc)[2][2][4][2], const Unit& u, int wr, int wc, int fr, int fq) {
;     ...
;                 for (int bj = 0; bj < 2; ++bj) { const int col = col0 + bj * HALF; float* xp = E.x + (size_t)row * DM + col; const float* xi = E.xin + (size_t)row * DM + col;
;                     f32x4 x0 = *(const f32x4*)xi, x1 = *(const f32x4*)(xi + 4); f32x4 v0 = acc[ai][bj][m][0], v1 = acc[ai][bj][m][1];
;                     if (ple) { const u32x4 pw = *(const u32x4*)(E.ppb + (size_t)row * DM + col); float pf[8]; unpack8(pw, pf);
; #pragma unroll
;                         for (int j = 0; j < 4; ++j) { x0[j] += sigmoidf_(v0[j] * rs) * pf[j] * E.alpha; x1[j] += sigmoidf_(v1[j] * rs) * pf[4 + j] * E.alpha; }
;                     } else if (E.cs) { const f32x4 c0 = *(const f32x4*)(E.cs + col), c1 = *(const f32x4*)(E.cs + col + 4); x0 += v0 * c0 * E.alpha; x1 += v1 * c1 * E.alpha; }
;                     else { x0 += v0 * E.alpha; x1 += v1 * E.alpha; }
;                     *(f32x4*)xp = x0; *(f32x4*)(xp + 4) = x1;
;                     u32x4 w; w.x = pk2(x0[0], x0[1]); w.y = pk2(x0[2], x0[3]); w.z = pk2(x1[0], x1[1]); w.w = pk2(x1[2], x1[3]);
;                     *(u32x4*)(E.xb + (size_t)row * DM + col) = w;
;                     sq += (x0[0] * x0[0] + x0[1] * x0[1]) + (x0[2] * x0[2] + x0[3] * x0[3]) + (x1[0] * x1[0] + x1[1] * x1[1]) + (x1[2] * x1[2] + x1[3] * x1[3]); }
;                 sq += __shfl_xor(sq, 16); sq += __shfl_xor(sq, 32);
;                 if (fq == 0) E.ss_out[(size_t)row * 16 + u.pn * 4 + wc] = sq; }
.LBB0_700:
	v_mul_f32_e32 v24, v131, v131
	v_fmac_f32_e32 v24, v130, v130
	v_mul_f32_e32 v130, v133, v133
	v_fmac_f32_e32 v130, v132, v132
	v_add_f32_e32 v24, v24, v130
	v_mul_f32_e32 v130, v135, v135
	v_fmac_f32_e32 v130, v134, v134
	v_add_f32_e32 v24, v130, v24
	v_mul_f32_e32 v130, v137, v137
	v_fmac_f32_e32 v130, v136, v136
	v_add_f32_e32 v24, v130, v24
	v_mul_f32_e32 v130, v143, v143
	v_mul_f32_e32 v131, v145, v145
	v_fmac_f32_e32 v130, v142, v142
	v_fmac_f32_e32 v131, v144, v144
	v_add_f32_e32 v130, v130, v131
	v_mul_f32_e32 v131, v147, v147
	v_fmac_f32_e32 v131, v146, v146
	v_add_f32_e32 v130, v131, v130
	v_mul_f32_e32 v131, v149, v149
	v_fmac_f32_e32 v131, v148, v148
	v_add_f32_e32 v130, v131, v130
	v_add_f32_e32 v24, v24, v130
	ds_bpermute_b32 v130, v217, v24
	v_cvt_pk_bf16_f32 v132, v142, v143
	v_cvt_pk_bf16_f32 v133, v144, v145
	v_cvt_pk_bf16_f32 v134, v146, v147
	v_cvt_pk_bf16_f32 v135, v148, v149
	s_waitcnt lgkmcnt(0)
	v_add_f32_e32 v24, v24, v130
	ds_bpermute_b32 v130, v216, v24
	global_store_dwordx4 v[180:181], v[142:145], off offset:512 nt
	global_store_dwordx4 v[180:181], v[146:149], off offset:528 nt
	global_store_dwordx4 v[182:183], v[132:135], off offset:256
	s_and_saveexec_b64 s[10:11], s[38:39]
	s_cbranch_execz .LBB0_702
	v_lshl_add_u64 v[132:133], s[6:7], 0, v[178:179]
	s_waitcnt lgkmcnt(0)
	v_add_f32_e32 v24, v24, v130
	global_store_dword v[132:133], v24, off

; DI unsigned pk2(float lo, float hi) { const f32x2v v = {lo, hi}; const bf16x2v b = __builtin_convertvector(v, bf16x2v); return __builtin_bit_cast(unsigned, b); }
; DI float sigmoidf_(float x) { return __builtin_amdgcn_rcpf(1.0f + __expf(-x)); }
; DI void unpack8(const u32x4& w, float* f) { f[0] = bflo(w.x); f[1] = bfhi(w.x); f[2] = bflo(w.y); f[3] = bfhi(w.y); f[4] = bflo(w.z); f[5] = bfhi(w.z); f[6] = bflo(w.w); f[7] = bfhi(w.w); }
; DI float rs_of(float ss, float inv_n) { return __builtin_amdgcn_rsqf(ss * inv_n + EPS); }
; DI float sum16_fq(const float* p, int fq) { const f32x4 a = *(const f32x4*)(p + 4 * fq); float s = (a[0] + a[1]) + (a[2] + a[3]); s += __shfl_xor(s, 16); s += __shfl_xor(s, 32); return s; }
; DI void epilogue(int kind, int l, const f32x4 (&acc)[2][2][4][2], const Unit& u, int wr, int wc, int fr, int fq) {
;     ...
;             for (int m = 0; m < 4; ++m) { const int row = row0 + ai * HALF + m * 16; float sq = 0.f;
;                 const float rs = ple ? rs_of(sum16_fq(E.ss_in + (size_t)row * 16, fq), 1.f / 1024.f) : 0.f;
; #pragma unroll
;                 for (int bj = 0; bj < 2; ++bj) { const int col = col0 + bj * HALF; float* xp = E.x + (size_t)row * DM + col; const float* xi = E.xin + (size_t)row * DM + col;
;                     f32x4 x0 = *(const f32x4*)xi, x1 = *(const f32x4*)(xi + 4); f32x4 v0 = acc[ai][bj][m][0], v1 = acc[ai][bj][m][1];
;                     if (ple) { const u32x4 pw = *(const u32x4*)(E.ppb + (size_t)row * DM + col); float pf[8]; unpack8(pw, pf);
; #pragma unroll
;                         for (int j = 0; j < 4; ++j) { x0[j] += sigmoidf_(v0[j] * rs) * pf[j] * E.alpha; x1[j] += sigmoidf_(v1[j] * rs) * pf[4 + j] * E.alpha; }
;                     } else if (E.cs) { const f32x4 c0 = *(const f32x4*)(E.cs + col), c1 = *(const f32x4*)(E.cs + col + 4); x0 += v0 * c0 * E.alpha; x1 += v1 * c1 * E.alpha; }
;                     else { x0 += v0 * E.alpha; x1 += v1 * E.alpha; }
;                     *(f32x4*)xp = x0; *(f32x4*)(xp + 4) = x1;
;                     u32x4 w; w.x = pk2(x0[0], x0[1]); w.y = pk2(x0[2], x0[3]); w.z = pk2(x1[0], x1[1]); w.w = pk2(x1[2], x1[3]);
;                     *(u32x4*)(E.xb + (size_t)row * DM + col) = w;
;                     sq += (x0[0] * x0[0] + x0[1] * x0[1]) + (x0[2] * x0[2] + x0[3] * x0[3]) + (x1[0] * x1[0] + x1[1] * x1[1]) + (x1[2] * x1[2] + x1[3] * x1[3]); }
.LBB0_711:
	s_waitcnt vmcnt(1)
	v_lshlrev_b64 v[138:139], 10, v[150:151]
	v_lshl_add_u64 v[140:141], v[138:139], 2, s[90:91]
	s_waitcnt vmcnt(0)
	v_lshl_add_u64 v[142:143], v[138:139], 1, s[8:9]
	v_lshl_add_u64 v[180:181], v[174:175], 2, v[140:141]
	v_cvt_pk_bf16_f32 v138, v130, v131
	v_cvt_pk_bf16_f32 v139, v132, v133
	v_cvt_pk_bf16_f32 v140, v134, v135
	v_cvt_pk_bf16_f32 v141, v136, v137
	v_lshl_add_u64 v[182:183], v[174:175], 1, v[142:143]
	global_store_dwordx4 v[180:181], v[130:133], off nt
	global_store_dwordx4 v[180:181], v[134:137], off offset:16 nt
	global_store_dwordx4 v[182:183], v[138:141], off
	global_load_dwordx4 v[138:141], v[152:153], off offset:528
	s_nop 0
	global_load_dwordx4 v[150:153], v[152:153], off offset:512
	s_and_b64 vcc, exec, s[46:47]
	s_mov_b64 s[10:11], -1
	s_cbranch_vccnz .LBB0_716
	s_and_b64 vcc, exec, s[42:43]
	s_cbranch_vccnz .LBB0_822
	v_lshl_add_u64 v[146:147], v[174:175], 2, s[94:95]
	global_load_dwordx4 v[142:145], v[146:147], off offset:512
	s_nop 0
	global_load_dwordx4 v[146:149], v[146:147], off offset:528
	s_mov_b32 s10, s92
	s_mov_b32 s11, s92
	s_waitcnt vmcnt(1)
	v_pk_mul_f32 v[144:145], v[88:89], v[144:145]
	v_pk_mul_f32 v[142:143], v[86:87], v[142:143]
	s_waitcnt vmcnt(0)
	v_pk_mul_f32 v[148:149], v[84:85], v[148:149]
	v_pk_mul_f32 v[146:147], v[82:83], v[146:147]
	v_pk_fma_f32 v[144:145], s[10:11], v[144:145], v[152:153]
	v_pk_fma_f32 v[142:143], s[92:93], v[142:143], v[150:151]
	v_pk_fma_f32 v[148:149], s[10:11], v[148:149], v[140:141]
	v_pk_fma_f32 v[146:147], s[92:93], v[146:147], v[138:139]
	s_cbranch_execnz .LBB0_715

; DI unsigned pk2(float lo, float hi) { const f32x2v v = {lo, hi}; const bf16x2v b = __builtin_convertvector(v, bf16x2v); return __builtin_bit_cast(unsigned, b); }
; DI float sigmoidf_(float x) { return __builtin_amdgcn_rcpf(1.0f + __expf(-x)); }
; DI void unpack8(const u32x4& w, float* f) { f[0] = bflo(w.x); f[1] = bfhi(w.x); f[2] = bflo(w.y); f[3] = bfhi(w.y); f[4] = bflo(w.z); f[5] = bfhi(w.z); f[6] = bflo(w.w); f[7] = bfhi(w.w); }
; DI float rs_of(float ss, float inv_n) { return __builtin_amdgcn_rsqf(ss * inv_n + EPS); }
; DI float sum16_fq(const float* p, int fq) { const f32x4 a = *(const f32x4*)(p + 4 * fq); float s = (a[0] + a[1]) + (a[2] + a[3]); s += __shfl_xor(s, 16); s += __shfl_xor(s, 32); return s; }
; DI void epilogue(int kind, int l, const f32x4 (&acc)[2][2][4][2], const Unit& u, int wr, int wc, int fr, int fq) {
;     ...
;             for (int m = 0; m < 4; ++m) { const int row = row0 + ai * HALF + m * 16; float sq = 0.f;
;                 const float rs = ple ? rs_of(sum16_fq(E.ss_in + (size_t)row * 16, fq), 1.f / 1024.f) : 0.f;
; #pragma unroll
;                 for (int bj = 0; bj < 2; ++bj) { const int col = col0 + bj * HALF; float* xp = E.x + (size_t)row * DM + col; const float* xi = E.xin + (size_t)row * DM + col;
;                     f32x4 x0 = *(const f32x4*)xi, x1 = *(const f32x4*)(xi + 4); f32x4 v0 = acc[ai][bj][m][0], v1 = acc[ai][bj][m][1];
;                     if (ple) { const u32x4 pw = *(const u32x4*)(E.ppb + (size_t)row * DM + col); float pf[8]; unpack8(pw, pf);
; #pragma unroll
;                         for (int j = 0; j < 4; ++j) { x0[j] += sigmoidf_(v0[j] * rs) * pf[j] * E.alpha; x1[j] += sigmoidf_(v1[j] * rs) * pf[4 + j] * E.alpha; }
;                     } else if (E.cs) { const f32x4 c0 = *(const f32x4*)(E.cs + col), c1 = *(const f32x4*)(E.cs + col + 4); x0 += v0 * c0 * E.alpha; x1 += v1 * c1 * E.alpha; }
;                     else { x0 += v0 * E.alpha; x1 += v1 * E.alpha; }
;                     *(f32x4*)xp = x0; *(f32x4*)(xp + 4) = x1;
;                     u32x4 w; w.x = pk2(x0[0], x0[1]); w.y = pk2(x0[2], x0[3]); w.z = pk2(x1[0], x1[1]); w.w = pk2(x1[2], x1[3]);
;                     *(u32x4*)(E.xb + (size_t)row * DM + col) = w;
;                     sq += (x0[0] * x0[0] + x0[1] * x0[1]) + (x0[2] * x0[2] + x0[3] * x0[3]) + (x1[0] * x1[0] + x1[1] * x1[1]) + (x1[2] * x1[2] + x1[3] * x1[3]); }
.LBB0_729:
	s_waitcnt vmcnt(1)
	v_lshlrev_b64 v[138:139], 10, v[150:151]
	v_lshl_add_u64 v[140:141], v[138:139], 2, s[90:91]
	s_waitcnt vmcnt(0)
	v_lshl_add_u64 v[142:143], v[138:139], 1, s[8:9]
	v_lshl_add_u64 v[180:181], v[174:175], 2, v[140:141]
	v_cvt_pk_bf16_f32 v138, v130, v131
	v_cvt_pk_bf16_f32 v139, v132, v133
	v_cvt_pk_bf16_f32 v140, v134, v135
	v_cvt_pk_bf16_f32 v141, v136, v137
	v_lshl_add_u64 v[182:183], v[174:175], 1, v[142:143]
	global_store_dwordx4 v[180:181], v[130:133], off nt
	global_store_dwordx4 v[180:181], v[134:137], off offset:16 nt
	global_store_dwordx4 v[182:183], v[138:141], off
	global_load_dwordx4 v[138:141], v[152:153], off offset:528
	s_nop 0
	global_load_dwordx4 v[150:153], v[152:153], off offset:512
	s_and_b64 vcc, exec, s[46:47]
	s_mov_b64 s[10:11], -1
	s_cbranch_vccnz .LBB0_734
	s_and_b64 vcc, exec, s[42:43]
	s_cbranch_vccnz .LBB0_824
	v_lshl_add_u64 v[146:147], v[174:175], 2, s[94:95]
	global_load_dwordx4 v[142:145], v[146:147], off offset:512
	s_nop 0
	global_load_dwordx4 v[146:149], v[146:147], off offset:528
	s_mov_b32 s10, s92
	s_mov_b32 s11, s92
	s_waitcnt vmcnt(1)
	v_pk_mul_f32 v[144:145], v[72:73], v[144:145]
	v_pk_mul_f32 v[142:143], v[70:71], v[142:143]
	s_waitcnt vmcnt(0)
	v_pk_mul_f32 v[148:149], v[68:69], v[148:149]
	v_pk_mul_f32 v[146:147], v[66:67], v[146:147]
	v_pk_fma_f32 v[144:145], s[10:11], v[144:145], v[152:153]
	v_pk_fma_f32 v[142:143], s[92:93], v[142:143], v[150:151]
	v_pk_fma_f32 v[148:149], s[10:11], v[148:149], v[140:141]
	v_pk_fma_f32 v[146:147], s[92:93], v[146:147], v[138:139]
	s_cbranch_execnz .LBB0_733

; DI unsigned pk2(float lo, float hi) { const f32x2v v = {lo, hi}; const bf16x2v b = __builtin_convertvector(v, bf16x2v); return __builtin_bit_cast(unsigned, b); }
; DI float sigmoidf_(float x) { return __builtin_amdgcn_rcpf(1.0f + __expf(-x)); }
; DI void unpack8(const u32x4& w, float* f) { f[0] = bflo(w.x); f[1] = bfhi(w.x); f[2] = bflo(w.y); f[3] = bfhi(w.y); f[4] = bflo(w.z); f[5] = bfhi(w.z); f[6] = bflo(w.w); f[7] = bfhi(w.w); }
; DI float rs_of(float ss, float inv_n) { return __builtin_amdgcn_rsqf(ss * inv_n + EPS); }
; DI float sum16_fq(const float* p, int fq) { const f32x4 a = *(const f32x4*)(p + 4 * fq); float s = (a[0] + a[1]) + (a[2] + a[3]); s += __shfl_xor(s, 16); s += __shfl_xor(s, 32); return s; }
; DI void epilogue(int kind, int l, const f32x4 (&acc)[2][2][4][2], const Unit& u, int wr, int wc, int fr, int fq) {
;     ...
;             for (int m = 0; m < 4; ++m) { const int row = row0 + ai * HALF + m * 16; float sq = 0.f;
;                 const float rs = ple ? rs_of(sum16_fq(E.ss_in + (size_t)row * 16, fq), 1.f / 1024.f) : 0.f;
; #pragma unroll
;                 for (int bj = 0; bj < 2; ++bj) { const int col = col0 + bj * HALF; float* xp = E.x + (size_t)row * DM + col; const float* xi = E.xin + (size_t)row * DM + col;
;                     f32x4 x0 = *(const f32x4*)xi, x1 = *(const f32x4*)(xi + 4); f32x4 v0 = acc[ai][bj][m][0], v1 = acc[ai][bj][m][1];
;                     if (ple) { const u32x4 pw = *(const u32x4*)(E.ppb + (size_t)row * DM + col); float pf[8]; unpack8(pw, pf);
; #pragma unroll
;                         for (int j = 0; j < 4; ++j) { x0[j] += sigmoidf_(v0[j] * rs) * pf[j] * E.alpha; x1[j] += sigmoidf_(v1[j] * rs) * pf[4 + j] * E.alpha; }
;                     } else if (E.cs) { const f32x4 c0 = *(const f32x4*)(E.cs + col), c1 = *(const f32x4*)(E.cs + col + 4); x0 += v0 * c0 * E.alpha; x1 += v1 * c1 * E.alpha; }
;                     else { x0 += v0 * E.alpha; x1 += v1 * E.alpha; }
;                     *(f32x4*)xp = x0; *(f32x4*)(xp + 4) = x1;
;                     u32x4 w; w.x = pk2(x0[0], x0[1]); w.y = pk2(x0[2], x0[3]); w.z = pk2(x1[0], x1[1]); w.w = pk2(x1[2], x1[3]);
;                     *(u32x4*)(E.xb + (size_t)row * DM + col) = w;
;                     sq += (x0[0] * x0[0] + x0[1] * x0[1]) + (x0[2] * x0[2] + x0[3] * x0[3]) + (x1[0] * x1[0] + x1[1] * x1[1]) + (x1[2] * x1[2] + x1[3] * x1[3]); }
.LBB0_747:
	s_waitcnt vmcnt(1)
	v_lshlrev_b64 v[138:139], 10, v[150:151]
	v_lshl_add_u64 v[140:141], v[138:139], 2, s[90:91]
	s_waitcnt vmcnt(0)
	v_lshl_add_u64 v[142:143], v[138:139], 1, s[8:9]
	v_lshl_add_u64 v[180:181], v[174:175], 2, v[140:141]
	v_cvt_pk_bf16_f32 v138, v130, v131
	v_cvt_pk_bf16_f32 v139, v132, v133
	v_cvt_pk_bf16_f32 v140, v134, v135
	v_cvt_pk_bf16_f32 v141, v136, v137
	v_lshl_add_u64 v[182:183], v[174:175], 1, v[142:143]
	global_store_dwordx4 v[180:181], v[130:133], off nt
	global_store_dwordx4 v[180:181], v[134:137], off offset:16 nt
	global_store_dwordx4 v[182:183], v[138:141], off
	global_load_dwordx4 v[138:141], v[152:153], off offset:528
	s_nop 0
	global_load_dwordx4 v[150:153], v[152:153], off offset:512
	s_and_b64 vcc, exec, s[46:47]
	s_mov_b64 s[10:11], -1
	s_cbranch_vccnz .LBB0_752
	s_and_b64 vcc, exec, s[42:43]
	s_cbranch_vccnz .LBB0_826
	v_lshl_add_u64 v[146:147], v[174:175], 2, s[94:95]
	global_load_dwordx4 v[142:145], v[146:147], off offset:512
	s_nop 0
	global_load_dwordx4 v[146:149], v[146:147], off offset:528
	s_mov_b32 s10, s92
	s_mov_b32 s11, s92
	s_waitcnt vmcnt(1)
	v_pk_mul_f32 v[144:145], v[56:57], v[144:145]
	v_pk_mul_f32 v[142:143], v[54:55], v[142:143]
	s_waitcnt vmcnt(0)
	v_pk_mul_f32 v[148:149], v[52:53], v[148:149]
	v_pk_mul_f32 v[146:147], v[50:51], v[146:147]
	v_pk_fma_f32 v[144:145], s[10:11], v[144:145], v[152:153]
	v_pk_fma_f32 v[142:143], s[92:93], v[142:143], v[150:151]
	v_pk_fma_f32 v[148:149], s[10:11], v[148:149], v[140:141]
	v_pk_fma_f32 v[146:147], s[92:93], v[146:147], v[138:139]
	s_cbranch_execnz .LBB0_751

; DI unsigned pk2(float lo, float hi) { const f32x2v v = {lo, hi}; const bf16x2v b = __builtin_convertvector(v, bf16x2v); return __builtin_bit_cast(unsigned, b); }
; DI float sigmoidf_(float x) { return __builtin_amdgcn_rcpf(1.0f + __expf(-x)); }
; DI void unpack8(const u32x4& w, float* f) { f[0] = bflo(w.x); f[1] = bfhi(w.x); f[2] = bflo(w.y); f[3] = bfhi(w.y); f[4] = bflo(w.z); f[5] = bfhi(w.z); f[6] = bflo(w.w); f[7] = bfhi(w.w); }
; DI float rs_of(float ss, float inv_n) { return __builtin_amdgcn_rsqf(ss * inv_n + EPS); }
; DI float sum16_fq(const float* p, int fq) { const f32x4 a = *(const f32x4*)(p + 4 * fq); float s = (a[0] + a[1]) + (a[2] + a[3]); s += __shfl_xor(s, 16); s += __shfl_xor(s, 32); return s; }
; DI void epilogue(int kind, int l, const f32x4 (&acc)[2][2][4][2], const Unit& u, int wr, int wc, int fr, int fq) {
;     ...
;             for (int m = 0; m < 4; ++m) { const int row = row0 + ai * HALF + m * 16; float sq = 0.f;
;                 const float rs = ple ? rs_of(sum16_fq(E.ss_in + (size_t)row * 16, fq), 1.f / 1024.f) : 0.f;
; #pragma unroll
;                 for (int bj = 0; bj < 2; ++bj) { const int col = col0 + bj * HALF; float* xp = E.x + (size_t)row * DM + col; const float* xi = E.xin + (size_t)row * DM + col;
;                     f32x4 x0 = *(const f32x4*)xi, x1 = *(const f32x4*)(xi + 4); f32x4 v0 = acc[ai][bj][m][0], v1 = acc[ai][bj][m][1];
;                     if (ple) { const u32x4 pw = *(const u32x4*)(E.ppb + (size_t)row * DM + col); float pf[8]; unpack8(pw, pf);
; #pragma unroll
;                         for (int j = 0; j < 4; ++j) { x0[j] += sigmoidf_(v0[j] * rs) * pf[j] * E.alpha; x1[j] += sigmoidf_(v1[j] * rs) * pf[4 + j] * E.alpha; }
;                     } else if (E.cs) { const f32x4 c0 = *(const f32x4*)(E.cs + col), c1 = *(const f32x4*)(E.cs + col + 4); x0 += v0 * c0 * E.alpha; x1 += v1 * c1 * E.alpha; }
;                     else { x0 += v0 * E.alpha; x1 += v1 * E.alpha; }
;                     *(f32x4*)xp = x0; *(f32x4*)(xp + 4) = x1;
;                     u32x4 w; w.x = pk2(x0[0], x0[1]); w.y = pk2(x0[2], x0[3]); w.z = pk2(x1[0], x1[1]); w.w = pk2(x1[2], x1[3]);
;                     *(u32x4*)(E.xb + (size_t)row * DM + col) = w;
;                     sq += (x0[0] * x0[0] + x0[1] * x0[1]) + (x0[2] * x0[2] + x0[3] * x0[3]) + (x1[0] * x1[0] + x1[1] * x1[1]) + (x1[2] * x1[2] + x1[3] * x1[3]); }
.LBB0_765:
	s_waitcnt vmcnt(1)
	v_lshlrev_b64 v[138:139], 10, v[150:151]
	v_lshl_add_u64 v[140:141], v[138:139], 2, s[90:91]
	s_waitcnt vmcnt(0)
	v_lshl_add_u64 v[142:143], v[138:139], 1, s[8:9]
	v_lshl_add_u64 v[180:181], v[174:175], 2, v[140:141]
	v_cvt_pk_bf16_f32 v138, v130, v131
	v_cvt_pk_bf16_f32 v139, v132, v133
	v_cvt_pk_bf16_f32 v140, v134, v135
	v_cvt_pk_bf16_f32 v141, v136, v137
	v_lshl_add_u64 v[182:183], v[174:175], 1, v[142:143]
	global_store_dwordx4 v[180:181], v[130:133], off nt
	global_store_dwordx4 v[180:181], v[134:137], off offset:16 nt
	global_store_dwordx4 v[182:183], v[138:141], off
	global_load_dwordx4 v[138:141], v[152:153], off offset:528
	s_nop 0
	global_load_dwordx4 v[150:153], v[152:153], off offset:512
	s_and_b64 vcc, exec, s[46:47]
	s_mov_b64 s[10:11], -1
	s_cbranch_vccnz .LBB0_770
	s_and_b64 vcc, exec, s[42:43]
	s_cbranch_vccnz .LBB0_828
	v_lshl_add_u64 v[146:147], v[174:175], 2, s[94:95]
	global_load_dwordx4 v[142:145], v[146:147], off offset:512
	s_nop 0
	global_load_dwordx4 v[146:149], v[146:147], off offset:528
	s_mov_b32 s10, s92
	s_mov_b32 s11, s92
	s_waitcnt vmcnt(1)
	v_pk_mul_f32 v[144:145], v[40:41], v[144:145]
	v_pk_mul_f32 v[142:143], v[38:39], v[142:143]
	s_waitcnt vmcnt(0)
	v_pk_mul_f32 v[148:149], v[36:37], v[148:149]
	v_pk_mul_f32 v[146:147], v[34:35], v[146:147]
	v_pk_fma_f32 v[144:145], s[10:11], v[144:145], v[152:153]
	v_pk_fma_f32 v[142:143], s[92:93], v[142:143], v[150:151]
	v_pk_fma_f32 v[148:149], s[10:11], v[148:149], v[140:141]
	v_pk_fma_f32 v[146:147], s[92:93], v[146:147], v[138:139]
	s_cbranch_execnz .LBB0_769

; DI unsigned pk2(float lo, float hi) { const f32x2v v = {lo, hi}; const bf16x2v b = __builtin_convertvector(v, bf16x2v); return __builtin_bit_cast(unsigned, b); }
; DI float sigmoidf_(float x) { return __builtin_amdgcn_rcpf(1.0f + __expf(-x)); }
; DI void unpack8(const u32x4& w, float* f) { f[0] = bflo(w.x); f[1] = bfhi(w.x); f[2] = bflo(w.y); f[3] = bfhi(w.y); f[4] = bflo(w.z); f[5] = bfhi(w.z); f[6] = bflo(w.w); f[7] = bfhi(w.w); }
; DI float rs_of(float ss, float inv_n) { return __builtin_amdgcn_rsqf(ss * inv_n + EPS); }
; DI float sum16_fq(const float* p, int fq) { const f32x4 a = *(const f32x4*)(p + 4 * fq); float s = (a[0] + a[1]) + (a[2] + a[3]); s += __shfl_xor(s, 16); s += __shfl_xor(s, 32); return s; }
; DI void epilogue(int kind, int l, const f32x4 (&acc)[2][2][4][2], const Unit& u, int wr, int wc, int fr, int fq) {
;     ...
;             for (int m = 0; m < 4; ++m) { const int row = row0 + ai * HALF + m * 16; float sq = 0.f;
;                 const float rs = ple ? rs_of(sum16_fq(E.ss_in + (size_t)row * 16, fq), 1.f / 1024.f) : 0.f;
; #pragma unroll
;                 for (int bj = 0; bj < 2; ++bj) { const int col = col0 + bj * HALF; float* xp = E.x + (size_t)row * DM + col; const float* xi = E.xin + (size_t)row * DM + col;
;                     f32x4 x0 = *(const f32x4*)xi, x1 = *(const f32x4*)(xi + 4); f32x4 v0 = acc[ai][bj][m][0], v1 = acc[ai][bj][m][1];
;                     if (ple) { const u32x4 pw = *(const u32x4*)(E.ppb + (size_t)row * DM + col); float pf[8]; unpack8(pw, pf);
; #pragma unroll
;                         for (int j = 0; j < 4; ++j) { x0[j] += sigmoidf_(v0[j] * rs) * pf[j] * E.alpha; x1[j] += sigmoidf_(v1[j] * rs) * pf[4 + j] * E.alpha; }
;                     } else if (E.cs) { const f32x4 c0 = *(const f32x4*)(E.cs + col), c1 = *(const f32x4*)(E.cs + col + 4); x0 += v0 * c0 * E.alpha; x1 += v1 * c1 * E.alpha; }
;                     else { x0 += v0 * E.alpha; x1 += v1 * E.alpha; }
;                     *(f32x4*)xp = x0; *(f32x4*)(xp + 4) = x1;
;                     u32x4 w; w.x = pk2(x0[0], x0[1]); w.y = pk2(x0[2], x0[3]); w.z = pk2(x1[0], x1[1]); w.w = pk2(x1[2], x1[3]);
;                     *(u32x4*)(E.xb + (size_t)row * DM + col) = w;
;                     sq += (x0[0] * x0[0] + x0[1] * x0[1]) + (x0[2] * x0[2] + x0[3] * x0[3]) + (x1[0] * x1[0] + x1[1] * x1[1]) + (x1[2] * x1[2] + x1[3] * x1[3]); }
.LBB0_783:
	s_waitcnt vmcnt(1)
	v_lshlrev_b64 v[138:139], 10, v[150:151]
	v_lshl_add_u64 v[140:141], v[138:139], 2, s[90:91]
	s_waitcnt vmcnt(0)
	v_lshl_add_u64 v[142:143], v[138:139], 1, s[8:9]
	v_lshl_add_u64 v[180:181], v[174:175], 2, v[140:141]
	v_cvt_pk_bf16_f32 v138, v130, v131
	v_cvt_pk_bf16_f32 v139, v132, v133
	v_cvt_pk_bf16_f32 v140, v134, v135
	v_cvt_pk_bf16_f32 v141, v136, v137
	v_lshl_add_u64 v[182:183], v[174:175], 1, v[142:143]
	global_store_dwordx4 v[180:181], v[130:133], off nt
	global_store_dwordx4 v[180:181], v[134:137], off offset:16 nt
	global_store_dwordx4 v[182:183], v[138:141], off
	global_load_dwordx4 v[138:141], v[152:153], off offset:528
	s_nop 0
	global_load_dwordx4 v[150:153], v[152:153], off offset:512
	s_and_b64 vcc, exec, s[46:47]
	s_mov_b64 s[10:11], -1
	s_cbranch_vccnz .LBB0_788
	s_and_b64 vcc, exec, s[42:43]
	s_cbranch_vccnz .LBB0_830
	v_lshl_add_u64 v[146:147], v[174:175], 2, s[94:95]
	global_load_dwordx4 v[142:145], v[146:147], off offset:512
	s_nop 0
	global_load_dwordx4 v[146:149], v[146:147], off offset:528
	s_mov_b32 s10, s92
	s_mov_b32 s11, s92
	s_waitcnt vmcnt(1)
	v_pk_mul_f32 v[144:145], v[22:23], v[144:145]
	v_pk_mul_f32 v[142:143], v[20:21], v[142:143]
	s_waitcnt vmcnt(0)
	v_pk_mul_f32 v[148:149], v[18:19], v[148:149]
	v_pk_mul_f32 v[146:147], v[16:17], v[146:147]
	v_pk_fma_f32 v[144:145], s[10:11], v[144:145], v[152:153]
	v_pk_fma_f32 v[142:143], s[92:93], v[142:143], v[150:151]
	v_pk_fma_f32 v[148:149], s[10:11], v[148:149], v[140:141]
	v_pk_fma_f32 v[146:147], s[92:93], v[146:147], v[138:139]
	s_cbranch_execnz .LBB0_787

; DI unsigned pk2(float lo, float hi) { const f32x2v v = {lo, hi}; const bf16x2v b = __builtin_convertvector(v, bf16x2v); return __builtin_bit_cast(unsigned, b); }
; DI float sigmoidf_(float x) { return __builtin_amdgcn_rcpf(1.0f + __expf(-x)); }
; DI void unpack8(const u32x4& w, float* f) { f[0] = bflo(w.x); f[1] = bfhi(w.x); f[2] = bflo(w.y); f[3] = bfhi(w.y); f[4] = bflo(w.z); f[5] = bfhi(w.z); f[6] = bflo(w.w); f[7] = bfhi(w.w); }
; DI float rs_of(float ss, float inv_n) { return __builtin_amdgcn_rsqf(ss * inv_n + EPS); }
; DI float sum16_fq(const float* p, int fq) { const f32x4 a = *(const f32x4*)(p + 4 * fq); float s = (a[0] + a[1]) + (a[2] + a[3]); s += __shfl_xor(s, 16); s += __shfl_xor(s, 32); return s; }
; DI void epilogue(int kind, int l, const f32x4 (&acc)[2][2][4][2], const Unit& u, int wr, int wc, int fr, int fq) {
;     ...
;             for (int m = 0; m < 4; ++m) { const int row = row0 + ai * HALF + m * 16; float sq = 0.f;
;                 const float rs = ple ? rs_of(sum16_fq(E.ss_in + (size_t)row * 16, fq), 1.f / 1024.f) : 0.f;
; #pragma unroll
;                 for (int bj = 0; bj < 2; ++bj) { const int col = col0 + bj * HALF; float* xp = E.x + (size_t)row * DM + col; const float* xi = E.xin + (size_t)row * DM + col;
;                     f32x4 x0 = *(const f32x4*)xi, x1 = *(const f32x4*)(xi + 4); f32x4 v0 = acc[ai][bj][m][0], v1 = acc[ai][bj][m][1];
;                     if (ple) { const u32x4 pw = *(const u32x4*)(E.ppb + (size_t)row * DM + col); float pf[8]; unpack8(pw, pf);
; #pragma unroll
;                         for (int j = 0; j < 4; ++j) { x0[j] += sigmoidf_(v0[j] * rs) * pf[j] * E.alpha; x1[j] += sigmoidf_(v1[j] * rs) * pf[4 + j] * E.alpha; }
;                     } else if (E.cs) { const f32x4 c0 = *(const f32x4*)(E.cs + col), c1 = *(const f32x4*)(E.cs + col + 4); x0 += v0 * c0 * E.alpha; x1 += v1 * c1 * E.alpha; }
;                     else { x0 += v0 * E.alpha; x1 += v1 * E.alpha; }
;                     *(f32x4*)xp = x0; *(f32x4*)(xp + 4) = x1;
;                     u32x4 w; w.x = pk2(x0[0], x0[1]); w.y = pk2(x0[2], x0[3]); w.z = pk2(x1[0], x1[1]); w.w = pk2(x1[2], x1[3]);
;                     *(u32x4*)(E.xb + (size_t)row * DM + col) = w;
;                     sq += (x0[0] * x0[0] + x0[1] * x0[1]) + (x0[2] * x0[2] + x0[3] * x0[3]) + (x1[0] * x1[0] + x1[1] * x1[1]) + (x1[2] * x1[2] + x1[3] * x1[3]); }
.LBB0_801:
	s_waitcnt vmcnt(1)
	v_lshlrev_b64 v[138:139], 10, v[150:151]
	v_lshl_add_u64 v[140:141], v[138:139], 2, s[90:91]
	s_waitcnt vmcnt(0)
	v_lshl_add_u64 v[142:143], v[138:139], 1, s[8:9]
	v_lshl_add_u64 v[176:177], v[174:175], 2, v[140:141]
	v_cvt_pk_bf16_f32 v138, v130, v131
	v_cvt_pk_bf16_f32 v139, v132, v133
	v_cvt_pk_bf16_f32 v140, v134, v135
	v_cvt_pk_bf16_f32 v141, v136, v137
	v_lshl_add_u64 v[180:181], v[174:175], 1, v[142:143]
	global_store_dwordx4 v[176:177], v[130:133], off
	global_store_dwordx4 v[176:177], v[134:137], off offset:16
	global_store_dwordx4 v[180:181], v[138:141], off nt
	global_load_dwordx4 v[138:141], v[152:153], off offset:528
	s_nop 0
	global_load_dwordx4 v[150:153], v[152:153], off offset:512
	s_and_b64 vcc, exec, s[46:47]
	s_mov_b64 s[4:5], -1
	v_readlane_b32 s46, v255, 54
	v_readlane_b32 s47, v255, 55
	s_cbranch_vccnz .LBB0_806
	s_and_b64 vcc, exec, s[42:43]
	s_cbranch_vccnz .LBB0_832
	v_lshl_add_u64 v[146:147], v[174:175], 2, s[94:95]
	global_load_dwordx4 v[142:145], v[146:147], off offset:512
	s_nop 0
	global_load_dwordx4 v[146:149], v[146:147], off offset:528
	s_mov_b32 s4, s92
	s_mov_b32 s5, s92
	s_waitcnt vmcnt(1)
	v_pk_mul_f32 v[144:145], v[6:7], v[144:145]
	v_pk_mul_f32 v[142:143], v[4:5], v[142:143]
	s_waitcnt vmcnt(0)
	v_pk_mul_f32 v[148:149], v[2:3], v[148:149]
	v_pk_mul_f32 v[146:147], v[0:1], v[146:147]
	v_pk_fma_f32 v[144:145], s[4:5], v[144:145], v[152:153]
	v_pk_fma_f32 v[142:143], s[92:93], v[142:143], v[150:151]
	v_pk_fma_f32 v[148:149], s[4:5], v[148:149], v[140:141]
	v_pk_fma_f32 v[146:147], s[92:93], v[146:147], v[138:139]
	s_cbranch_execnz .LBB0_805

; DI unsigned pk2(float lo, float hi) { const f32x2v v = {lo, hi}; const bf16x2v b = __builtin_convertvector(v, bf16x2v); return __builtin_bit_cast(unsigned, b); }
; DI float sigmoidf_(float x) { return __builtin_amdgcn_rcpf(1.0f + __expf(-x)); }
; DI void unpack8(const u32x4& w, float* f) { f[0] = bflo(w.x); f[1] = bfhi(w.x); f[2] = bflo(w.y); f[3] = bfhi(w.y); f[4] = bflo(w.z); f[5] = bfhi(w.z); f[6] = bflo(w.w); f[7] = bfhi(w.w); }
; DI void epilogue(int kind, int l, const f32x4 (&acc)[2][2][4][2], const Unit& u, int wr, int wc, int fr, int fq) {
;     ...
;                 for (int bj = 0; bj < 2; ++bj) { const int col = col0 + bj * HALF; float* xp = E.x + (size_t)row * DM + col; const float* xi = E.xin + (size_t)row * DM + col;
;                     f32x4 x0 = *(const f32x4*)xi, x1 = *(const f32x4*)(xi + 4); f32x4 v0 = acc[ai][bj][m][0], v1 = acc[ai][bj][m][1];
;                     if (ple) { const u32x4 pw = *(const u32x4*)(E.ppb + (size_t)row * DM + col); float pf[8]; unpack8(pw, pf);
; #pragma unroll
;                         for (int j = 0; j < 4; ++j) { x0[j] += sigmoidf_(v0[j] * rs) * pf[j] * E.alpha; x1[j] += sigmoidf_(v1[j] * rs) * pf[4 + j] * E.alpha; }
;                     } else if (E.cs) { const f32x4 c0 = *(const f32x4*)(E.cs + col), c1 = *(const f32x4*)(E.cs + col + 4); x0 += v0 * c0 * E.alpha; x1 += v1 * c1 * E.alpha; }
;                     else { x0 += v0 * E.alpha; x1 += v1 * E.alpha; }
;                     *(f32x4*)xp = x0; *(f32x4*)(xp + 4) = x1;
;                     u32x4 w; w.x = pk2(x0[0], x0[1]); w.y = pk2(x0[2], x0[3]); w.z = pk2(x1[0], x1[1]); w.w = pk2(x1[2], x1[3]);
;                     *(u32x4*)(E.xb + (size_t)row * DM + col) = w;
;                     sq += (x0[0] * x0[0] + x0[1] * x0[1]) + (x0[2] * x0[2] + x0[3] * x0[3]) + (x1[0] * x1[0] + x1[1] * x1[1]) + (x1[2] * x1[2] + x1[3] * x1[3]); }
;                 sq += __shfl_xor(sq, 16); sq += __shfl_xor(sq, 32);
;                 if (fq == 0) E.ss_out[(size_t)row * 16 + u.pn * 4 + wc] = sq; }
.LBB0_808:
	v_mul_f32_e32 v24, v131, v131
	v_fmac_f32_e32 v24, v130, v130
	v_mul_f32_e32 v130, v133, v133
	v_fmac_f32_e32 v130, v132, v132
	v_add_f32_e32 v24, v24, v130
	v_mul_f32_e32 v130, v135, v135
	v_fmac_f32_e32 v130, v134, v134
	v_add_f32_e32 v24, v130, v24
	v_mul_f32_e32 v130, v137, v137
	v_fmac_f32_e32 v130, v136, v136
	v_add_f32_e32 v24, v130, v24
	v_mul_f32_e32 v130, v143, v143
	v_mul_f32_e32 v131, v145, v145
	v_fmac_f32_e32 v130, v142, v142
	v_fmac_f32_e32 v131, v144, v144
	v_add_f32_e32 v130, v130, v131
	v_mul_f32_e32 v131, v147, v147
	v_fmac_f32_e32 v131, v146, v146
	v_add_f32_e32 v130, v131, v130
	v_mul_f32_e32 v131, v149, v149
	v_fmac_f32_e32 v131, v148, v148
	v_add_f32_e32 v130, v131, v130
	v_add_f32_e32 v24, v24, v130
	ds_bpermute_b32 v130, v217, v24
	v_cvt_pk_bf16_f32 v132, v142, v143
	v_cvt_pk_bf16_f32 v133, v144, v145
	v_cvt_pk_bf16_f32 v134, v146, v147
	v_cvt_pk_bf16_f32 v135, v148, v149
	s_waitcnt lgkmcnt(0)
	v_add_f32_e32 v24, v24, v130
	ds_bpermute_b32 v130, v216, v24
	global_store_dwordx4 v[176:177], v[142:145], off offset:512
	global_store_dwordx4 v[176:177], v[146:149], off offset:528
	global_store_dwordx4 v[180:181], v[132:135], off offset:256 nt
	s_and_saveexec_b64 s[4:5], s[38:39]
	s_cbranch_execz .LBB0_810
	v_lshl_add_u64 v[132:133], s[6:7], 0, v[178:179]
	s_waitcnt lgkmcnt(0)
	v_add_f32_e32 v24, v24, v130
	global_store_dword v[132:133], v24, off
